# hyena step loop: in-range path falls through from step to step (out-of-range paths moved out of line), removing one taken branch per in-range step
# baseline (speedup 1.0000x reference)
; __device__ __forceinline__ void hyena_lat_job(const Params& p, char* smem, int l, int c) {
;     ...
;       for (int g8 = 0; g8 < 8; ++g8) {
;         HY_STEP(0, bq0, bq1) HY_STEP(1, bq1, bq0) HY_STEP(2, bq0, bq1) HY_STEP(3, bq1, bq0)
;         HY_STEP(4, bq0, bq1) HY_STEP(5, bq1, bq0) HY_STEP(6, bq0, bq1) HY_STEP(7, bq1, bq0)
;       }
.LBB0_997:
	s_sub_i32 s35, s34, s18
	v_add_u32_e32 v146, s31, v142
	v_add_u32_e32 v147, s31, v141
	v_add_u32_e32 v149, s31, v140
	v_add_u32_e32 v148, s31, v139
	s_cmp_gt_u32 s35, s50
	s_cbranch_scc1 .Lhy_skip0
	s_waitcnt lgkmcnt(4)
	v_mfma_f32_32x32x16_bf16 v[50:65], v[66:69], v[98:101], v[50:65]
	ds_read_b128 v[66:69], v147 offset:43008
	ds_read_b128 v[228:231], v241
	v_mfma_f32_32x32x16_bf16 v[34:49], v[86:89], v[98:101], v[34:49]
	v_add_u32_e32 v240, 4, v0
	v_cmp_gt_u32_e32 vcc, s55, v240
	v_add_u32_e32 v241, 0xa0, v242
	v_mfma_f32_32x32x16_bf16 v[18:33], v[70:73], v[98:101], v[18:33]
	s_waitcnt lgkmcnt(5)
	v_mfma_f32_32x32x16_bf16 v[2:17], v[82:85], v[98:101], v[2:17]
	v_cndmask_b32_e32 v241, 64, v241, vcc
.Lhy_next0:
	s_add_i32 s16, s35, 1
	s_cmp_gt_u32 s16, s50
	s_cbranch_scc1 .Lhy_skip1
	s_waitcnt lgkmcnt(4)
	v_mfma_f32_32x32x16_bf16 v[50:65], v[78:81], v[102:105], v[50:65]
	ds_read_b128 v[78:81], v149 offset:43264
	ds_read_b128 v[98:101], v241
	v_mfma_f32_32x32x16_bf16 v[34:49], v[90:93], v[102:105], v[34:49]
	v_add_u32_e32 v240, 3, v0
	v_cmp_gt_u32_e32 vcc, s55, v240
	v_add_u32_e32 v241, 0x70, v242
	v_mfma_f32_32x32x16_bf16 v[18:33], v[74:77], v[102:105], v[18:33]
	s_waitcnt lgkmcnt(5)
	v_mfma_f32_32x32x16_bf16 v[2:17], v[94:97], v[102:105], v[2:17]
	v_cndmask_b32_e32 v241, 64, v241, vcc
.Lhy_next1:
	s_add_i32 s16, s35, 2
	s_cmp_gt_u32 s16, s50
	s_cbranch_scc1 .Lhy_skip2
	s_waitcnt lgkmcnt(4)
	v_mfma_f32_32x32x16_bf16 v[50:65], v[86:89], v[224:227], v[50:65]
	ds_read_b128 v[86:89], v148 offset:43520
	ds_read_b128 v[102:105], v241
	v_mfma_f32_32x32x16_bf16 v[34:49], v[70:73], v[224:227], v[34:49]
	v_add_u32_e32 v240, 2, v0
	v_cmp_gt_u32_e32 vcc, s55, v240
	v_add_u32_e32 v241, 0x50, v242
	v_mfma_f32_32x32x16_bf16 v[18:33], v[82:85], v[224:227], v[18:33]
	s_waitcnt lgkmcnt(5)
	v_mfma_f32_32x32x16_bf16 v[2:17], v[66:69], v[224:227], v[2:17]
	v_cndmask_b32_e32 v241, 64, v241, vcc
.Lhy_next2:
	s_add_i32 s16, s35, 3
	s_cmp_gt_u32 s16, s50
	s_cbranch_scc1 .Lhy_skip3
	s_waitcnt lgkmcnt(4)
	v_mfma_f32_32x32x16_bf16 v[50:65], v[90:93], v[228:231], v[50:65]
	ds_read_b128 v[90:93], v146 offset:43776
	ds_read_b128 v[224:227], v241
	v_mfma_f32_32x32x16_bf16 v[34:49], v[74:77], v[228:231], v[34:49]
	v_add_u32_e32 v240, 1, v0
	v_cmp_gt_u32_e32 vcc, s55, v240
	v_add_u32_e32 v241, 32, v242
	v_mfma_f32_32x32x16_bf16 v[18:33], v[94:97], v[228:231], v[18:33]
	s_waitcnt lgkmcnt(5)
	v_mfma_f32_32x32x16_bf16 v[2:17], v[78:81], v[228:231], v[2:17]
	v_cndmask_b32_e32 v241, 64, v241, vcc
.Lhy_next3:
	s_add_i32 s16, s35, 4
	s_cmp_gt_u32 s16, s50
	s_cbranch_scc1 .Lhy_skip4
	s_waitcnt lgkmcnt(4)
	v_mfma_f32_32x32x16_bf16 v[50:65], v[70:73], v[98:101], v[50:65]
	ds_read_b128 v[70:73], v147 offset:44032
	ds_read_b128 v[228:231], v241
	v_mfma_f32_32x32x16_bf16 v[34:49], v[82:85], v[98:101], v[34:49]
	v_add_u32_e32 v240, 0, v0
	v_cmp_gt_u32_e32 vcc, s55, v240
	v_add_u32_e32 v241, 0, v242
	v_mfma_f32_32x32x16_bf16 v[18:33], v[66:69], v[98:101], v[18:33]
	s_waitcnt lgkmcnt(5)
	v_mfma_f32_32x32x16_bf16 v[2:17], v[86:89], v[98:101], v[2:17]
	v_cndmask_b32_e32 v241, 64, v241, vcc
.Lhy_next4:
	s_add_i32 s16, s35, 5
	s_cmp_gt_u32 s16, s50
	s_cbranch_scc1 .Lhy_skip5
	s_waitcnt lgkmcnt(4)
	v_mfma_f32_32x32x16_bf16 v[50:65], v[74:77], v[102:105], v[50:65]
	ds_read_b128 v[74:77], v149 offset:44288
	ds_read_b128 v[98:101], v241
	v_mfma_f32_32x32x16_bf16 v[34:49], v[94:97], v[102:105], v[34:49]
	v_add_u32_e32 v240, -1, v0
	v_cmp_gt_u32_e32 vcc, s55, v240
	v_add_u32_e32 v241, 0xffffffd0, v242
	v_mfma_f32_32x32x16_bf16 v[18:33], v[78:81], v[102:105], v[18:33]
	s_waitcnt lgkmcnt(5)
	v_mfma_f32_32x32x16_bf16 v[2:17], v[90:93], v[102:105], v[2:17]
	v_cndmask_b32_e32 v241, 64, v241, vcc
; __device__ __forceinline__ void hyena_lat_job(const Params& p, char* smem, int l, int c) {
;     ...
;       for (int g8 = 0; g8 < 8; ++g8) {
;         HY_STEP(0, bq0, bq1) HY_STEP(1, bq1, bq0) HY_STEP(2, bq0, bq1) HY_STEP(3, bq1, bq0)
;         HY_STEP(4, bq0, bq1) HY_STEP(5, bq1, bq0) HY_STEP(6, bq0, bq1) HY_STEP(7, bq1, bq0)
;       }
.Lhy_next5:
	s_add_i32 s16, s35, 6
	s_cmp_gt_u32 s16, s50
	s_cbranch_scc1 .Lhy_skip6
	s_waitcnt lgkmcnt(4)
	v_mfma_f32_32x32x16_bf16 v[50:65], v[82:85], v[224:227], v[50:65]
	ds_read_b128 v[82:85], v148 offset:44544
	ds_read_b128 v[102:105], v241
	v_mfma_f32_32x32x16_bf16 v[34:49], v[66:69], v[224:227], v[34:49]
	v_add_u32_e32 v240, -2, v0
	v_cmp_gt_u32_e32 vcc, s55, v240
	v_add_u32_e32 v241, 0xffffffb0, v242
	v_mfma_f32_32x32x16_bf16 v[18:33], v[86:89], v[224:227], v[18:33]
	s_waitcnt lgkmcnt(5)
	v_mfma_f32_32x32x16_bf16 v[2:17], v[70:73], v[224:227], v[2:17]
	v_cndmask_b32_e32 v241, 64, v241, vcc
.Lhy_next6:
	s_add_i32 s16, s35, 7
	s_cmp_gt_u32 s16, s50
	s_cbranch_scc1 .Lhy_skip7
	s_waitcnt lgkmcnt(4)
	v_mfma_f32_32x32x16_bf16 v[50:65], v[94:97], v[228:231], v[50:65]
	ds_read_b128 v[94:97], v146 offset:44800
	ds_read_b128 v[224:227], v241
	v_mfma_f32_32x32x16_bf16 v[34:49], v[78:81], v[228:231], v[34:49]
	v_add_u32_e32 v240, -3, v0
	v_cmp_gt_u32_e32 vcc, s55, v240
	v_add_u32_e32 v241, 0xffffff80, v242
	v_mfma_f32_32x32x16_bf16 v[18:33], v[90:93], v[228:231], v[18:33]
	s_waitcnt lgkmcnt(5)
	v_mfma_f32_32x32x16_bf16 v[2:17], v[74:77], v[228:231], v[2:17]
	v_cndmask_b32_e32 v241, 64, v241, vcc
.Lhy_next7:
	v_add_u32_e32 v242, 0xfffffec0, v242
	s_branch .LBB0_996
.Lhy_skip0:
	s_waitcnt lgkmcnt(6)
	ds_read_b128 v[66:69], v147 offset:43008
	ds_read_b128 v[228:231], v241
	v_add_u32_e32 v240, 4, v0
	v_cmp_gt_u32_e32 vcc, s55, v240
	v_add_u32_e32 v241, 0xa0, v242
	s_nop 1
	v_cndmask_b32_e32 v241, 64, v241, vcc
	s_branch .Lhy_next0
.Lhy_skip1:
	s_waitcnt lgkmcnt(6)
	ds_read_b128 v[78:81], v149 offset:43264
	ds_read_b128 v[98:101], v241
	v_add_u32_e32 v240, 3, v0
	v_cmp_gt_u32_e32 vcc, s55, v240
	v_add_u32_e32 v241, 0x70, v242
	s_nop 1
	v_cndmask_b32_e32 v241, 64, v241, vcc
	s_branch .Lhy_next1
.Lhy_skip2:
	s_waitcnt lgkmcnt(6)
	ds_read_b128 v[86:89], v148 offset:43520
	ds_read_b128 v[102:105], v241
	v_add_u32_e32 v240, 2, v0
	v_cmp_gt_u32_e32 vcc, s55, v240
	v_add_u32_e32 v241, 0x50, v242
	s_nop 1
	v_cndmask_b32_e32 v241, 64, v241, vcc
	s_branch .Lhy_next2
.Lhy_skip3:
	s_waitcnt lgkmcnt(6)
	ds_read_b128 v[90:93], v146 offset:43776
	ds_read_b128 v[224:227], v241
	v_add_u32_e32 v240, 1, v0
	v_cmp_gt_u32_e32 vcc, s55, v240
	v_add_u32_e32 v241, 32, v242
	s_nop 1
	v_cndmask_b32_e32 v241, 64, v241, vcc
	s_branch .Lhy_next3
.Lhy_skip4:
	s_waitcnt lgkmcnt(6)
	ds_read_b128 v[70:73], v147 offset:44032
	ds_read_b128 v[228:231], v241
	v_add_u32_e32 v240, 0, v0
	v_cmp_gt_u32_e32 vcc, s55, v240
	v_add_u32_e32 v241, 0, v242
	s_nop 1
	v_cndmask_b32_e32 v241, 64, v241, vcc
	s_branch .Lhy_next4
.Lhy_skip5:
	s_waitcnt lgkmcnt(6)
	ds_read_b128 v[74:77], v149 offset:44288
	ds_read_b128 v[98:101], v241
	v_add_u32_e32 v240, -1, v0
	v_cmp_gt_u32_e32 vcc, s55, v240
	v_add_u32_e32 v241, 0xffffffd0, v242
	s_nop 1
	v_cndmask_b32_e32 v241, 64, v241, vcc
	s_branch .Lhy_next5
.Lhy_skip6:
	s_waitcnt lgkmcnt(6)
	ds_read_b128 v[82:85], v148 offset:44544
	ds_read_b128 v[102:105], v241
	v_add_u32_e32 v240, -2, v0
	v_cmp_gt_u32_e32 vcc, s55, v240
	v_add_u32_e32 v241, 0xffffffb0, v242
	s_nop 1
	v_cndmask_b32_e32 v241, 64, v241, vcc
	s_branch .Lhy_next6
.Lhy_skip7:
	s_waitcnt lgkmcnt(6)
	ds_read_b128 v[94:97], v146 offset:44800
	ds_read_b128 v[224:227], v241
	v_add_u32_e32 v240, -3, v0
	v_cmp_gt_u32_e32 vcc, s55, v240
	v_add_u32_e32 v241, 0xffffff80, v242
	s_nop 1
	v_cndmask_b32_e32 v241, 64, v241, vcc
	s_branch .Lhy_next7
